# P9: static priority raise for the owner waves 0..3 (the other half was tried before and was slower)
# speedup vs baseline: 1.0028x; 1.0028x over previous
.LBB0_1059:
	s_cmp_lt_i32 s74, 10
	s_cselect_b64 s[0:1], -1, 0
	s_and_b64 s[40:41], s[0:1], s[2:3]
	s_andn2_b64 vcc, exec, s[40:41]
	s_cbranch_vccnz .LBB0_1203
	s_mov_b32 s101, 0
	s_mov_b32 s98, 0
	v_readfirstlane_b32 s0, v198
	s_nop 1
	s_lshr_b32 s0, s0, 6
	s_cmp_gt_u32 s0, 3
	s_cbranch_scc1 .Lp9_noprio
	s_setprio 1
.Lp9_noprio:
	v_readlane_b32 s0, v254, 23
	v_lshlrev_b32_e32 v1, 2, v199
	v_readlane_b32 s6, v254, 29
	v_readlane_b32 s7, v254, 30
	v_readlane_b32 s12, v254, 35
	v_readlane_b32 s13, v254, 36
	s_nop 2
	global_load_dword v2, v1, s[6:7]
	s_waitcnt lgkmcnt(0)
	global_load_dword v3, v1, s[12:13]
	global_load_dword v4, v1, s[12:13] offset:512
	v_mbcnt_lo_u32_b32 v1, -1, 0
	v_mbcnt_hi_u32_b32 v1, -1, v1
	v_and_b32_e32 v5, 64, v1
	v_xor_b32_e32 v6, 1, v1
	v_add_u32_e32 v5, 64, v5
	v_cmp_lt_i32_e32 vcc, v6, v5
	v_xor_b32_e32 v7, 2, v1
	v_xor_b32_e32 v8, 4, v1
	v_cndmask_b32_e32 v6, v1, v6, vcc
	v_lshlrev_b32_e32 v6, 2, v6
	v_cmp_lt_i32_e32 vcc, v7, v5
	v_xor_b32_e32 v9, 8, v1
	v_xor_b32_e32 v10, 16, v1
	v_cndmask_b32_e32 v7, v1, v7, vcc
	v_lshlrev_b32_e32 v7, 2, v7
	v_cmp_lt_i32_e32 vcc, v8, v5
	v_xor_b32_e32 v11, 32, v1
	s_add_u32 s46, s72, 0x70000
	v_cndmask_b32_e32 v8, v1, v8, vcc
	v_lshlrev_b32_e32 v8, 2, v8
	v_cmp_lt_i32_e32 vcc, v9, v5
	s_addc_u32 s47, s73, 0
	s_cmpk_lt_u32 s76, 0x100
	v_cndmask_b32_e32 v9, v1, v9, vcc
	v_lshlrev_b32_e32 v9, 2, v9
	v_cmp_lt_i32_e32 vcc, v10, v5
	v_readlane_b32 s2, v254, 25
	v_readlane_b32 s3, v254, 26
	s_cselect_b64 s[50:51], -1, 0
	s_cmpk_gt_u32 s76, 0xff
	v_readlane_b32 s4, v254, 27
	s_cselect_b64 s[2:3], -1, 0
	s_mov_b32 s4, -1
	v_readlane_b32 s1, v254, 24
	v_readlane_b32 s5, v254, 28
	v_readlane_b32 s8, v254, 31
	v_readlane_b32 s9, v254, 32
	v_readlane_b32 s10, v254, 33
	v_readlane_b32 s11, v254, 34
	v_readlane_b32 s14, v254, 37
	v_readlane_b32 s15, v254, 38
	s_waitcnt vmcnt(0)
	v_and_b32_e32 v12, 0x7fffffff, v2
	v_and_b32_e32 v13, 0x7fffffff, v3
	v_and_b32_e32 v14, 0x7fffffff, v4
	ds_bpermute_b32 v12, v6, v12
	ds_bpermute_b32 v13, v6, v13
	ds_bpermute_b32 v6, v6, v14
	v_max_f32_e64 v2, |v2|, |v2|
	v_max_f32_e64 v3, |v3|, |v3|
	v_max_f32_e64 v4, |v4|, |v4|
	s_waitcnt lgkmcnt(2)
	v_max_f32_e32 v12, v12, v12
	s_waitcnt lgkmcnt(1)
	v_max_f32_e32 v13, v13, v13
	s_waitcnt lgkmcnt(0)
	v_max_f32_e32 v6, v6, v6
	v_max_f32_e32 v2, v2, v12
	v_max_f32_e32 v3, v3, v13
	v_max_f32_e32 v4, v4, v6
	ds_bpermute_b32 v6, v7, v2
	ds_bpermute_b32 v12, v7, v3
	ds_bpermute_b32 v7, v7, v4
	s_waitcnt lgkmcnt(2)
	v_max_f32_e32 v6, v6, v6
	s_waitcnt lgkmcnt(1)
	v_max_f32_e32 v12, v12, v12
	s_waitcnt lgkmcnt(0)
	v_max_f32_e32 v7, v7, v7
	v_max_f32_e32 v2, v2, v6
	v_max_f32_e32 v3, v3, v12
	v_max_f32_e32 v4, v4, v7
	ds_bpermute_b32 v6, v8, v2
	ds_bpermute_b32 v7, v8, v3
	ds_bpermute_b32 v8, v8, v4
	s_waitcnt lgkmcnt(2)
	v_max_f32_e32 v6, v6, v6
	s_waitcnt lgkmcnt(1)
	v_max_f32_e32 v7, v7, v7
	s_waitcnt lgkmcnt(0)
	v_max_f32_e32 v8, v8, v8
	v_max_f32_e32 v2, v2, v6
	v_max_f32_e32 v3, v3, v7
	v_max_f32_e32 v4, v4, v8
	ds_bpermute_b32 v6, v9, v2
	ds_bpermute_b32 v7, v9, v3
	ds_bpermute_b32 v8, v9, v4
	v_cndmask_b32_e32 v9, v1, v10, vcc
	v_lshlrev_b32_e32 v9, 2, v9
	s_waitcnt lgkmcnt(2)
	v_max_f32_e32 v6, v6, v6
	s_waitcnt lgkmcnt(1)
	v_max_f32_e32 v7, v7, v7
	s_waitcnt lgkmcnt(0)
	v_max_f32_e32 v8, v8, v8
	v_max_f32_e32 v2, v2, v6
	v_max_f32_e32 v3, v3, v7
	v_max_f32_e32 v4, v4, v8
	ds_bpermute_b32 v6, v9, v2
	ds_bpermute_b32 v7, v9, v3
	ds_bpermute_b32 v8, v9, v4
	v_cmp_lt_i32_e32 vcc, v11, v5
	s_waitcnt lgkmcnt(1)
	v_max_f32_e32 v5, v7, v7
	v_cndmask_b32_e32 v1, v1, v11, vcc
	v_lshlrev_b32_e32 v207, 2, v1
	v_max_f32_e32 v1, v6, v6
	s_waitcnt lgkmcnt(0)
	v_max_f32_e32 v6, v8, v8
	v_max_f32_e32 v2, v2, v1
	v_max_f32_e32 v1, v3, v5
	v_max_f32_e32 v181, v4, v6
	ds_bpermute_b32 v4, v207, v2
	ds_bpermute_b32 v3, v207, v1
	ds_bpermute_b32 v204, v207, v181
	s_and_b64 vcc, exec, s[2:3]
	s_cbranch_vccnz .LBB0_1068
	v_cmp_eq_u32_e32 vcc, 0, v199
	s_cmpk_eq_i32 s33, 0x100
	s_cbranch_scc1 .Lp9_static_idx
	v_mov_b32_e32 v5, -1
	s_and_saveexec_b64 s[4:5], vcc
	s_cbranch_execz .LBB0_1065
	s_mov_b64 s[8:9], exec
	v_mbcnt_lo_u32_b32 v5, s8, 0
	v_mbcnt_hi_u32_b32 v5, s9, v5
	v_cmp_eq_u32_e64 s[0:1], 0, v5
	s_and_saveexec_b64 s[6:7], s[0:1]
	s_cbranch_execz .LBB0_1064
	s_bcnt1_i32_b64 s0, s[8:9]
	v_mov_b32_e32 v6, 0
	v_mov_b32_e32 v7, s0
	global_atomic_add v6, v6, v7, s[46:47] sc0

.LBB0_1203:
	s_setprio 0
	s_cmp_gt_i32 s75, 10
	s_cselect_b64 s[0:1], -1, 0
	s_and_b64 s[2:3], s[40:41], s[0:1]
	s_andn2_b64 vcc, exec, s[2:3]
	s_cbranch_vccnz .LBB0_1257
	s_waitcnt vmcnt(0)
	s_waitcnt vmcnt(0) lgkmcnt(0)
	s_barrier
	s_mov_b64 s[2:3], exec
	v_readlane_b32 s4, v254, 5
	v_readlane_b32 s5, v254, 6
	s_and_b64 s[4:5], s[2:3], s[4:5]
	s_mov_b64 exec, s[4:5]
	s_cbranch_execz .LBB0_1256
	s_add_i32 s4, 0, 0x23fc0
	v_mov_b32_e32 v1, s4
	s_waitcnt vmcnt(0) expcnt(0) lgkmcnt(0)
	ds_read_b32 v3, v1
	s_add_i32 s4, 0, 0x23fc4
	v_mov_b32_e32 v1, s4
	ds_read_b32 v1, v1
	s_waitcnt lgkmcnt(1)
	v_cmp_ne_u32_e32 vcc, 0, v3
	s_cbranch_vccnz .LBB0_1220
	v_readlane_b32 s4, v254, 0
	v_readlane_b32 s5, v254, 1
	s_load_dwordx2 s[8:9], s[4:5], 0x4
	s_add_u32 s4, s72, 0x71200
	s_addc_u32 s5, s73, 0
	s_add_u32 s6, s72, 0x71400
	s_addc_u32 s7, s73, 0
	s_waitcnt lgkmcnt(0)
	s_mul_i32 s42, s8, s33
	s_add_u32 s8, s72, 0x71500
	s_mul_i32 s42, s42, s9
	s_addc_u32 s9, s73, 0
	s_add_u32 s10, s72, 0x71600
	s_addc_u32 s11, s73, 0
	s_add_u32 s12, s72, 0x71700
	s_addc_u32 s13, s73, 0
	s_add_u32 s14, s72, 0x71800
	s_addc_u32 s15, s73, 0
	s_add_u32 s16, s72, 0x71900
	s_addc_u32 s17, s73, 0
	s_add_u32 s18, s72, 0x71a00
	s_addc_u32 s19, s73, 0
	s_add_u32 s20, s72, 0x71b00
	s_addc_u32 s21, s73, 0
	s_add_u32 s22, s72, 0x71c00
	s_addc_u32 s23, s73, 0
	s_add_u32 s24, s72, 0x71d00
	s_addc_u32 s25, s73, 0
	s_add_u32 s26, s72, 0x71e00
	s_addc_u32 s27, s73, 0
	s_add_u32 s28, s72, 0x71f00
	s_addc_u32 s29, s73, 0
	s_add_u32 s30, s72, 0x72000
	s_addc_u32 s31, s73, 0
	s_add_u32 s34, s72, 0x72100
	s_addc_u32 s35, s73, 0
	s_add_u32 s36, s72, 0x72200
	s_addc_u32 s37, s73, 0
	s_add_u32 s40, s72, 0x72300
	s_addc_u32 s41, s73, 0
	s_mov_b32 s43, 1
	v_mov_b32_e32 v17, 0
	s_branch .LBB0_1208
